# RWKV scan: per-chunk LDS operand base addresses precomputed once per scan (3 fewer VALU per chunk), on top of the trim pack
# speedup vs baseline: 1.0100x; 1.0008x over previous
; DI void phase_scan(const Params& p, char* smem) {
;     ...
;   const int tid = tid__, lane = tid & 63, wave = tid >> 6, kq = lane & 15, rg = lane >> 4;
;   const int chain = (blk & 7) + 8 * (blk >> 5), quarter = (blk >> 3) & 3;
;   const int b = chain >> 3, h = (chain >> 1) & 3, dir = chain & 1;
;   const u16* sc = (const u16*)(p.ws + OFF_R3);
;   const size_t AS = (size_t)NT * 256;
;   const u16* aOMW = sc + (dir ? SA_OMWB : SA_OMWF) * AS;
;   const u16* aKD = sc + (dir ? SA_KDB : SA_KDF) * AS;
;   const u16* aB = sc + (dir ? SA_BB : SA_BF) * AS;
;   const u16* aKKN = sc + SA_KKN * AS;
;   const u16* aR = sc + SA_R * AS;
;   const u16* aV = sc + SA_V * AS;
;   u16* Y = (u16*)(p.ws + OFF_R2) + (dir ? AS : 0);
;   constexpr int CH = 16, BSZ = 5 * CH * 64 + CH * 16;
;   float* buf = (float*)smem;
;   const int st_ld = tid >> 4, k4 = (tid & 15) * 4;
;   const int vrow = quarter * 16 + wave * 4 + rg;
;   uint2 g0, g1, g2, g3, g4; u16 gv;
;     ...
;   float2_t S01 = {0.f, 0.f}, S23 = {0.f, 0.f};
;   __builtin_amdgcn_s_setprio(3);
;   __syncthreads();
;   SCAN_GLOAD(0); SCAN_LSTORE(0);
;   __syncthreads();
;   constexpr int NCH = LK / CH;
.LBB0_506:
	s_or_b64 exec, exec, s[4:5]
	s_and_b64 s[4:5], s[0:1], exec
	s_cselect_b32 s4, s77, 0x8800000
	s_add_u32 s42, s22, s4
	s_addc_u32 s43, s23, 0
	s_mul_i32 s7, s7, 0x1100000
	s_add_u32 s4, s22, s7
	s_addc_u32 s5, s23, 0
	s_add_u32 s80, s4, 0x2200000
	s_addc_u32 s81, s5, 0
	s_and_b64 s[4:5], s[0:1], exec
	s_cselect_b32 s4, s3, 0x9900000
	s_add_u32 s40, s22, s4
	s_addc_u32 s41, s23, 0
	s_and_b64 s[4:5], s[0:1], exec
	s_cselect_b32 s4, 0, 0x1100000
	v_readlane_b32 s8, v254, 63
	v_readlane_b32 s9, v255, 0
	s_add_u32 s4, s8, s4
	s_addc_u32 s5, s9, 0
	s_lshl_b32 s7, s6, 1
	s_waitcnt vmcnt(0)
	v_ashrrev_i32_e32 v5, 31, v4
	s_lshl_b32 s6, s6, 5
	v_and_b32_e32 v18, 15, v14
	v_lshlrev_b64 v[20:21], 8, v[4:5]
	s_and_b32 s55, s6, 0xc0
	v_lshlrev_b32_e32 v2, 2, v18
	v_or_b32_e32 v20, s55, v20
	v_or_b32_e32 v4, v20, v2
	v_mov_b32_e32 v5, v21
	v_lshlrev_b64 v[12:13], 1, v[4:5]
	v_lshl_add_u64 v[4:5], s[42:43], 0, v[12:13]
	flat_load_dwordx2 v[4:5], v[4:5]
	v_lshl_add_u64 v[6:7], s[80:81], 0, v[12:13]
	v_readlane_b32 s8, v253, 39
	s_and_b32 s7, s7, 48
	v_and_b32_e32 v25, -4, v3
	flat_load_dwordx2 v[6:7], v[6:7]
	v_lshl_add_u64 v[8:9], s[40:41], 0, v[12:13]
	v_readlane_b32 s9, v253, 40
	v_bfe_u32 v24, v14, 4, 2
	v_add_u32_e32 v0, s7, v25
	flat_load_dwordx2 v[8:9], v[8:9]
	v_lshl_add_u64 v[10:11], s[8:9], 0, v[12:13]
	v_lshl_add_u64 v[20:21], v[20:21], 1, s[26:27]
	s_lshl_b32 s64, s7, 1
	v_or_b32_e32 v16, v0, v24
	flat_load_dwordx2 v[10:11], v[10:11]
	v_lshl_add_u64 v[12:13], s[22:23], 0, v[12:13]
	v_lshl_add_u64 v[20:21], v[20:21], 0, s[64:65]
	v_lshlrev_b32_e32 v0, 1, v18
	flat_load_dwordx2 v[12:13], v[12:13]
	v_lshl_add_u64 v[20:21], v[20:21], 0, v[0:1]
	flat_load_ushort v27, v[20:21]
	v_lshlrev_b32_e32 v15, 4, v18
	v_lshl_or_b32 v26, v3, 8, v15
	v_and_b32_e32 v14, 0x3ffffff0, v14
	s_add_u32 s6, s26, s64
	s_addc_u32 s7, s27, 0
	v_ashrrev_i32_e32 v17, 31, v16
	v_cmp_eq_u32_e64 s[38:39], 15, v18
	s_nop 0
	s_nop 0
	v_cmp_eq_u32_e64 s[12:13], 4, v18
	v_cmp_eq_u32_e64 s[14:15], 5, v18
	v_cmp_eq_u32_e64 s[16:17], 6, v18
	v_cmp_eq_u32_e64 s[18:19], 7, v18
	v_cmp_eq_u32_e64 s[20:21], 8, v18
	v_cmp_eq_u32_e64 s[22:23], 9, v18
	v_cmp_eq_u32_e64 s[24:25], 10, v18
	v_cmp_eq_u32_e64 s[26:27], 11, v18
	v_cmp_eq_u32_e64 s[28:29], 13, v18
	v_cmp_eq_u32_e64 s[34:35], 12, v18
	v_cmp_eq_u32_e64 s[36:37], 14, v18
	s_mov_b32 s54, 0
	s_mov_b32 s64, -16
	s_mov_b32 s96, 0
	v_and_b32_e32 v52, 8, v2
	v_and_b32_e32 v53, 4, v2
	v_cmp_ne_u32_e64 s[8:9], 0, v52
	v_cmp_ne_u32_e64 s[10:11], 0, v53
	v_lshlrev_b32_e32 v35, 2, v25
	v_lshlrev_b32_e32 v36, 2, v24
	v_add_u32_e32 v35, v35, v36
	v_add_u32_e32 v35, 0x5000, v35
	v_lshlrev_b32_e32 v36, 2, v2
	s_waitcnt vmcnt(0) lgkmcnt(0)
	v_lshlrev_b32_e32 v20, 16, v4
	v_and_b32_e32 v21, 0xffff0000, v4
	v_pk_add_f32 v[28:29], v[20:21], 1.0 op_sel_hi:[1,0] neg_lo:[1,0] neg_hi:[1,0]
	v_lshlrev_b32_e32 v20, 16, v5
	v_and_b32_e32 v21, 0xffff0000, v5
	v_pk_add_f32 v[30:31], v[20:21], 1.0 op_sel_hi:[1,0] neg_lo:[1,0] neg_hi:[1,0]
	ds_write_b128 v26, v[28:31]
	v_lshlrev_b32_e32 v28, 16, v6
	v_and_b32_e32 v29, 0xffff0000, v6
	v_lshlrev_b32_e32 v30, 16, v7
	v_and_b32_e32 v31, 0xffff0000, v7
	ds_write_b128 v26, v[28:31] offset:4096
	v_lshlrev_b32_e32 v28, 16, v8
	v_and_b32_e32 v29, 0xffff0000, v8
	v_lshlrev_b32_e32 v30, 16, v9
	v_and_b32_e32 v31, 0xffff0000, v9
	ds_write_b128 v26, v[28:31] offset:8192
	v_lshlrev_b32_e32 v28, 16, v10
	v_and_b32_e32 v29, 0xffff0000, v10
	v_lshlrev_b32_e32 v30, 16, v11
	v_and_b32_e32 v31, 0xffff0000, v11
	ds_write_b128 v26, v[28:31] offset:12288
	v_lshlrev_b32_e32 v28, 16, v12
	v_and_b32_e32 v29, 0xffff0000, v12
	v_lshlrev_b32_e32 v30, 16, v13
	v_and_b32_e32 v31, 0xffff0000, v13
	ds_write_b128 v26, v[28:31] offset:16384
	v_lshlrev_b32_e32 v15, 16, v27
	v_lshl_or_b32 v28, v14, 2, v2
	ds_write_b32 v28, v15 offset:20480
	v_lshl_add_u64 v[14:15], s[6:7], 0, v[0:1]
	s_lshl_b32 s6, s55, 1
	s_add_u32 s4, s4, s6
	v_sub_u32_e32 v0, 0, v18
	s_addc_u32 s5, s5, 0
	v_cndmask_b32_e64 v0, v0, v18, s[0:1]
	v_lshl_add_u64 v[16:17], v[16:17], 1, s[4:5]
	v_cmp_eq_u32_e64 s[4:5], 0, v18
	v_cmp_eq_u32_e64 s[6:7], 1, v18
	v_mov_b32_e32 v18, 0
	v_sub_u32_e32 v29, 0, v3
	v_mov_b32_e32 v19, v18
	v_mov_b32_e32 v20, v18
	v_mov_b32_e32 v21, v18
	s_waitcnt lgkmcnt(0)
	s_barrier
	s_branch .LBB0_508

; DI void phase_scan(const Params& p, char* smem) {
;     ...
;     const float* bb = buf + (c & 1) * BSZ;
;     const int rowbase = scan_row(b, dir, c * CH);
;     const int rstep = dir ? -1 : 1;
;     const float* bl = bb + kq * 4;
;     const float* bv = bb + 5 * CH * 64 + wave * 4 + rg;
;     float4 fwv[3], fkv[3], fbv[3], fav[3], frv[3]; float vvv[3];
; #pragma unroll
;     for (int q = 0; q < 2; ++q) {
;       fwv[q] = *(const float4*)(bl + 0 * CH * 64 + q * 64); fkv[q] = *(const float4*)(bl + 1 * CH * 64 + q * 64); fbv[q] = *(const float4*)(bl + 2 * CH * 64 + q * 64);
;       fav[q] = *(const float4*)(bl + 3 * CH * 64 + q * 64); frv[q] = *(const float4*)(bl + 4 * CH * 64 + q * 64); vvv[q] = bv[q * 16];
;     }
;     float ysel = 0.f, ypart = 0.f;
; #pragma unroll
;     for (int s = 0; s < CH; ++s) {
;       const float4 fw = fwv[s % 3], fk = fkv[s % 3], fb = fbv[s % 3], fa = fav[s % 3], fr = frv[s % 3];
;       const float vv = vvv[s % 3];
;       const float2_t a01 = {fa.x, fa.y}, a23 = {fa.z, fa.w};
;       const float2_t w01 = {fw.x, fw.y}, w23 = {fw.z, fw.w}, k01 = {fk.x, fk.y}, k23 = {fk.z, fk.w}, b01 = {fb.x, fb.y}, b23 = {fb.z, fb.w};
;       const float2_t r01 = {fr.x, fr.y}, r23 = {fr.z, fr.w};
;       const float2_t vv2 = {vv, vv};
;       if (s + 2 < CH) {
;         constexpr int dummy = 0; (void)dummy;
;         const int q = (s + 2) % 3;
;         fwv[q] = *(const float4*)(bl + 0 * CH * 64 + (s + 2) * 64); fkv[q] = *(const float4*)(bl + 1 * CH * 64 + (s + 2) * 64); fbv[q] = *(const float4*)(bl + 2 * CH * 64 + (s + 2) * 64);
;         fav[q] = *(const float4*)(bl + 3 * CH * 64 + (s + 2) * 64); frv[q] = *(const float4*)(bl + 4 * CH * 64 + (s + 2) * 64); vvv[q] = bv[(s + 2) * 16];
;       }
;       float2_t t2 = S01 * a01; t2 = S23 * a23 + t2;
;       const float2_t q01 = S01 * w01 + vv2 * k01, q23 = S23 * w23 + vv2 * k23;
;       float xs = t2.x + t2.y, ys = ypart;
;       xs += __builtin_bit_cast(float, __builtin_amdgcn_update_dpp(0, __builtin_bit_cast(int, xs), 0x128, 0xf, 0xf, false));
;       ys += __builtin_bit_cast(float, __builtin_amdgcn_update_dpp(0, __builtin_bit_cast(int, ys), 0x128, 0xf, 0xf, false));
;       xs += __builtin_bit_cast(float, __builtin_amdgcn_update_dpp(0, __builtin_bit_cast(int, xs), 0x124, 0xf, 0xf, false));
.LBB0_512:
	s_bitcmp1_b32 s96, 0
	s_cselect_b32 s79, 0x5400, 0
	v_add_u32_e32 v32, s79, v35
	v_or_b32_e32 v31, s79, v36
	ds_read2_b32 v[164:165], v32 offset0:0 offset1:16
	ds_read2_b32 v[166:167], v32 offset0:32 offset1:48
	ds_read2_b32 v[168:169], v32 offset0:64 offset1:80
	ds_read2_b32 v[170:171], v32 offset0:96 offset1:112
	ds_read_b128 v[100:103], v31 offset:0
	ds_read_b128 v[104:107], v31 offset:4096
	ds_read_b128 v[108:111], v31 offset:8192
	ds_read_b128 v[112:115], v31 offset:12288
	ds_read_b128 v[116:119], v31 offset:16384
	ds_read_b128 v[120:123], v31 offset:256
	ds_read_b128 v[124:127], v31 offset:4352
	ds_read_b128 v[128:131], v31 offset:8448
	ds_read_b128 v[132:135], v31 offset:12544
	ds_read_b128 v[136:139], v31 offset:16640
	v_add_u32_e32 v30, v30, v0
	s_add_i32 s96, s96, 1
	s_andn2_b64 vcc, exec, s[46:47]
	s_waitcnt lgkmcnt(5)
	v_pk_mul_f32 v[42:43], v[114:115], v[20:21]
	v_pk_mul_f32 v[46:47], v[102:103], v[20:21]
	v_pk_fma_f32 v[42:43], v[112:113], v[18:19], v[42:43]
	v_pk_mul_f32 v[44:45], v[100:101], v[18:19]
	v_add_f32_e32 v48, v42, v43
	v_pk_fma_f32 v[44:45], v[104:105], v[164:165], v[44:45] op_sel_hi:[1,0,1]
	v_pk_fma_f32 v[46:47], v[106:107], v[164:165], v[46:47] op_sel_hi:[1,0,1]
	v_add_f32_dpp v48, v48, v48 row_ror:8 row_mask:0xf bank_mask:0xf bound_ctrl:1
	ds_read_b128 v[140:143], v31 offset:512
	ds_read_b128 v[144:147], v31 offset:4608
	v_add_f32_dpp v48, v48, v48 row_ror:4 row_mask:0xf bank_mask:0xf bound_ctrl:1
	ds_read_b128 v[148:151], v31 offset:8704
	ds_read_b128 v[152:155], v31 offset:12800
	v_add_f32_dpp v48, v48, v48 row_ror:2 row_mask:0xf bank_mask:0xf bound_ctrl:1
	ds_read_b128 v[156:159], v31 offset:16896
	s_nop 0
	v_add_f32_dpp v48, v48, v48 row_ror:1 row_mask:0xf bank_mask:0xf bound_ctrl:1
	v_pk_fma_f32 v[18:19], v[108:109], v[48:49], v[44:45] op_sel_hi:[1,0,1]
	v_pk_fma_f32 v[20:21], v[110:111], v[48:49], v[46:47] op_sel_hi:[1,0,1]
	s_waitcnt lgkmcnt(5)
	v_pk_mul_f32 v[42:43], v[134:135], v[20:21]
	v_pk_mul_f32 v[46:47], v[122:123], v[20:21]
	v_pk_fma_f32 v[42:43], v[132:133], v[18:19], v[42:43]
	v_pk_mul_f32 v[44:45], v[120:121], v[18:19]
	v_add_f32_e32 v48, v42, v43
	v_pk_fma_f32 v[44:45], v[124:125], v[164:165], v[44:45] op_sel:[0,1,0]
	v_pk_fma_f32 v[46:47], v[126:127], v[164:165], v[46:47] op_sel:[0,1,0]
	v_add_f32_dpp v48, v48, v48 row_ror:8 row_mask:0xf bank_mask:0xf bound_ctrl:1
	v_pk_mul_f32 v[50:51], v[116:117], v[18:19]
	v_pk_fma_f32 v[50:51], v[118:119], v[20:21], v[50:51]
	v_add_f32_dpp v48, v48, v48 row_ror:4 row_mask:0xf bank_mask:0xf bound_ctrl:1
	v_add_f32_e32 v180, v50, v51
	ds_read_b128 v[100:103], v31 offset:768
	v_add_f32_dpp v48, v48, v48 row_ror:2 row_mask:0xf bank_mask:0xf bound_ctrl:1
	ds_read_b128 v[104:107], v31 offset:4864
	ds_read_b128 v[108:111], v31 offset:8960
	v_add_f32_dpp v48, v48, v48 row_ror:1 row_mask:0xf bank_mask:0xf bound_ctrl:1
	ds_read_b128 v[112:115], v31 offset:13056
	ds_read_b128 v[116:119], v31 offset:17152
	v_pk_fma_f32 v[18:19], v[128:129], v[48:49], v[44:45] op_sel_hi:[1,0,1]
	v_pk_fma_f32 v[20:21], v[130:131], v[48:49], v[46:47] op_sel_hi:[1,0,1]
	s_waitcnt lgkmcnt(5)
	v_pk_mul_f32 v[42:43], v[154:155], v[20:21]
	v_pk_mul_f32 v[46:47], v[142:143], v[20:21]
	v_pk_fma_f32 v[42:43], v[152:153], v[18:19], v[42:43]
	v_pk_mul_f32 v[44:45], v[140:141], v[18:19]
	v_add_f32_e32 v48, v42, v43
	v_pk_fma_f32 v[44:45], v[144:145], v[166:167], v[44:45] op_sel_hi:[1,0,1]
	v_pk_fma_f32 v[46:47], v[146:147], v[166:167], v[46:47] op_sel_hi:[1,0,1]
	v_add_f32_dpp v48, v48, v48 row_ror:8 row_mask:0xf bank_mask:0xf bound_ctrl:1
	v_pk_mul_f32 v[50:51], v[136:137], v[18:19]
	v_pk_fma_f32 v[50:51], v[138:139], v[20:21], v[50:51]
	v_add_f32_dpp v48, v48, v48 row_ror:4 row_mask:0xf bank_mask:0xf bound_ctrl:1
	v_add_f32_e32 v181, v50, v51
	ds_read_b128 v[120:123], v31 offset:1024
	v_add_f32_dpp v48, v48, v48 row_ror:2 row_mask:0xf bank_mask:0xf bound_ctrl:1
	ds_read_b128 v[124:127], v31 offset:5120
	ds_read_b128 v[128:131], v31 offset:9216
	v_add_f32_dpp v48, v48, v48 row_ror:1 row_mask:0xf bank_mask:0xf bound_ctrl:1
	ds_read_b128 v[132:135], v31 offset:13312
	ds_read_b128 v[136:139], v31 offset:17408
	ds_read2_b32 v[172:173], v32 offset0:128 offset1:144
	ds_read2_b32 v[174:175], v32 offset0:160 offset1:176
	v_pk_fma_f32 v[18:19], v[148:149], v[48:49], v[44:45] op_sel_hi:[1,0,1]
	v_pk_fma_f32 v[20:21], v[150:151], v[48:49], v[46:47] op_sel_hi:[1,0,1]
	s_waitcnt lgkmcnt(7)
	v_pk_mul_f32 v[42:43], v[114:115], v[20:21]
	v_pk_mul_f32 v[46:47], v[102:103], v[20:21]
	v_pk_fma_f32 v[42:43], v[112:113], v[18:19], v[42:43]
	v_pk_mul_f32 v[44:45], v[100:101], v[18:19]
	v_add_f32_e32 v48, v42, v43
	v_pk_fma_f32 v[44:45], v[104:105], v[166:167], v[44:45] op_sel:[0,1,0]
	v_pk_fma_f32 v[46:47], v[106:107], v[166:167], v[46:47] op_sel:[0,1,0]
	v_add_f32_dpp v48, v48, v48 row_ror:8 row_mask:0xf bank_mask:0xf bound_ctrl:1
	v_pk_mul_f32 v[50:51], v[156:157], v[18:19]
	v_pk_fma_f32 v[50:51], v[158:159], v[20:21], v[50:51]
	v_add_f32_dpp v48, v48, v48 row_ror:4 row_mask:0xf bank_mask:0xf bound_ctrl:1
	v_add_f32_e32 v182, v50, v51
	ds_read_b128 v[140:143], v31 offset:1280
	v_add_f32_dpp v48, v48, v48 row_ror:2 row_mask:0xf bank_mask:0xf bound_ctrl:1
	ds_read_b128 v[144:147], v31 offset:5376
	ds_read_b128 v[148:151], v31 offset:9472
	v_add_f32_dpp v48, v48, v48 row_ror:1 row_mask:0xf bank_mask:0xf bound_ctrl:1
	ds_read_b128 v[152:155], v31 offset:13568
	ds_read_b128 v[156:159], v31 offset:17664
	ds_read2_b32 v[176:177], v32 offset0:192 offset1:208
	ds_read2_b32 v[178:179], v32 offset0:224 offset1:240
	v_pk_fma_f32 v[18:19], v[108:109], v[48:49], v[44:45] op_sel_hi:[1,0,1]
	v_pk_fma_f32 v[20:21], v[110:111], v[48:49], v[46:47] op_sel_hi:[1,0,1]
	s_waitcnt lgkmcnt(9)
; DI void phase_scan(const Params& p, char* smem) {
;     ...
;     for (int s = 0; s < CH; ++s) {
;       const float4 fw = fwv[s % 3], fk = fkv[s % 3], fb = fbv[s % 3], fa = fav[s % 3], fr = frv[s % 3];
;       const float vv = vvv[s % 3];
;       const float2_t a01 = {fa.x, fa.y}, a23 = {fa.z, fa.w};
;       const float2_t w01 = {fw.x, fw.y}, w23 = {fw.z, fw.w}, k01 = {fk.x, fk.y}, k23 = {fk.z, fk.w}, b01 = {fb.x, fb.y}, b23 = {fb.z, fb.w};
;       const float2_t r01 = {fr.x, fr.y}, r23 = {fr.z, fr.w};
;       const float2_t vv2 = {vv, vv};
;       if (s + 2 < CH) {
;         constexpr int dummy = 0; (void)dummy;
;         const int q = (s + 2) % 3;
;         fwv[q] = *(const float4*)(bl + 0 * CH * 64 + (s + 2) * 64); fkv[q] = *(const float4*)(bl + 1 * CH * 64 + (s + 2) * 64); fbv[q] = *(const float4*)(bl + 2 * CH * 64 + (s + 2) * 64);
;         fav[q] = *(const float4*)(bl + 3 * CH * 64 + (s + 2) * 64); frv[q] = *(const float4*)(bl + 4 * CH * 64 + (s + 2) * 64); vvv[q] = bv[(s + 2) * 16];
;       }
;       float2_t t2 = S01 * a01; t2 = S23 * a23 + t2;
;       const float2_t q01 = S01 * w01 + vv2 * k01, q23 = S23 * w23 + vv2 * k23;
;       float xs = t2.x + t2.y, ys = ypart;
;       xs += __builtin_bit_cast(float, __builtin_amdgcn_update_dpp(0, __builtin_bit_cast(int, xs), 0x128, 0xf, 0xf, false));
;       ys += __builtin_bit_cast(float, __builtin_amdgcn_update_dpp(0, __builtin_bit_cast(int, ys), 0x128, 0xf, 0xf, false));
;       xs += __builtin_bit_cast(float, __builtin_amdgcn_update_dpp(0, __builtin_bit_cast(int, xs), 0x124, 0xf, 0xf, false));
;       ys += __builtin_bit_cast(float, __builtin_amdgcn_update_dpp(0, __builtin_bit_cast(int, ys), 0x124, 0xf, 0xf, false));
;       xs += __builtin_bit_cast(float, __builtin_amdgcn_update_dpp(0, __builtin_bit_cast(int, xs), 0x122, 0xf, 0xf, false));
;       ys += __builtin_bit_cast(float, __builtin_amdgcn_update_dpp(0, __builtin_bit_cast(int, ys), 0x122, 0xf, 0xf, false));
;       xs += __builtin_bit_cast(float, __builtin_amdgcn_update_dpp(0, __builtin_bit_cast(int, xs), 0x121, 0xf, 0xf, false));
;       ys += __builtin_bit_cast(float, __builtin_amdgcn_update_dpp(0, __builtin_bit_cast(int, ys), 0x121, 0xf, 0xf, false));
;       if (s > 0) ysel = (kq == s - 1) ? ys : ysel;
;       const float2_t sa2 = {xs, xs};
;       S01 = sa2 * b01 + q01; S23 = sa2 * b23 + q23;
;       float2_t y2 = S01 * r01; y2 = S23 * r23 + y2;
	v_pk_mul_f32 v[42:43], v[134:135], v[20:21]
	v_pk_mul_f32 v[46:47], v[122:123], v[20:21]
	v_pk_fma_f32 v[42:43], v[132:133], v[18:19], v[42:43]
	v_pk_mul_f32 v[44:45], v[120:121], v[18:19]
	v_add_f32_e32 v48, v42, v43
	v_pk_fma_f32 v[44:45], v[124:125], v[168:169], v[44:45] op_sel_hi:[1,0,1]
	v_pk_fma_f32 v[46:47], v[126:127], v[168:169], v[46:47] op_sel_hi:[1,0,1]
	v_add_f32_dpp v48, v48, v48 row_ror:8 row_mask:0xf bank_mask:0xf bound_ctrl:1
	v_pk_mul_f32 v[50:51], v[116:117], v[18:19]
	v_pk_fma_f32 v[50:51], v[118:119], v[20:21], v[50:51]
	v_add_f32_dpp v48, v48, v48 row_ror:4 row_mask:0xf bank_mask:0xf bound_ctrl:1
	v_add_f32_e32 v183, v50, v51
	ds_read_b128 v[100:103], v31 offset:1536
	v_add_f32_dpp v48, v48, v48 row_ror:2 row_mask:0xf bank_mask:0xf bound_ctrl:1
	ds_read_b128 v[104:107], v31 offset:5632
	ds_read_b128 v[108:111], v31 offset:9728
	v_add_f32_dpp v48, v48, v48 row_ror:1 row_mask:0xf bank_mask:0xf bound_ctrl:1
	ds_read_b128 v[112:115], v31 offset:13824
	ds_read_b128 v[116:119], v31 offset:17920
	v_pk_fma_f32 v[18:19], v[128:129], v[48:49], v[44:45] op_sel_hi:[1,0,1]
	v_pk_fma_f32 v[20:21], v[130:131], v[48:49], v[46:47] op_sel_hi:[1,0,1]
	s_waitcnt lgkmcnt(7)
	v_pk_mul_f32 v[42:43], v[154:155], v[20:21]
	v_pk_mul_f32 v[46:47], v[142:143], v[20:21]
	v_pk_fma_f32 v[42:43], v[152:153], v[18:19], v[42:43]
	v_pk_mul_f32 v[44:45], v[140:141], v[18:19]
	v_add_f32_e32 v48, v42, v43
	v_pk_fma_f32 v[44:45], v[144:145], v[168:169], v[44:45] op_sel:[0,1,0]
	v_pk_fma_f32 v[46:47], v[146:147], v[168:169], v[46:47] op_sel:[0,1,0]
	v_add_f32_dpp v48, v48, v48 row_ror:8 row_mask:0xf bank_mask:0xf bound_ctrl:1
	v_pk_mul_f32 v[50:51], v[136:137], v[18:19]
	v_pk_fma_f32 v[50:51], v[138:139], v[20:21], v[50:51]
	v_add_f32_dpp v48, v48, v48 row_ror:4 row_mask:0xf bank_mask:0xf bound_ctrl:1
	v_add_f32_e32 v184, v50, v51
	ds_read_b128 v[120:123], v31 offset:1792
	v_add_f32_dpp v48, v48, v48 row_ror:2 row_mask:0xf bank_mask:0xf bound_ctrl:1
	ds_read_b128 v[124:127], v31 offset:5888
	ds_read_b128 v[128:131], v31 offset:9984
	v_add_f32_dpp v48, v48, v48 row_ror:1 row_mask:0xf bank_mask:0xf bound_ctrl:1
	ds_read_b128 v[132:135], v31 offset:14080
	ds_read_b128 v[136:139], v31 offset:18176
	v_pk_fma_f32 v[18:19], v[148:149], v[48:49], v[44:45] op_sel_hi:[1,0,1]
	v_pk_fma_f32 v[20:21], v[150:151], v[48:49], v[46:47] op_sel_hi:[1,0,1]
	s_waitcnt lgkmcnt(5)
	v_pk_mul_f32 v[42:43], v[114:115], v[20:21]
	v_pk_mul_f32 v[46:47], v[102:103], v[20:21]
	v_pk_fma_f32 v[42:43], v[112:113], v[18:19], v[42:43]
	v_pk_mul_f32 v[44:45], v[100:101], v[18:19]
	v_add_f32_e32 v48, v42, v43
	v_pk_fma_f32 v[44:45], v[104:105], v[170:171], v[44:45] op_sel_hi:[1,0,1]
	v_pk_fma_f32 v[46:47], v[106:107], v[170:171], v[46:47] op_sel_hi:[1,0,1]
	v_add_f32_dpp v48, v48, v48 row_ror:8 row_mask:0xf bank_mask:0xf bound_ctrl:1
	v_pk_mul_f32 v[50:51], v[156:157], v[18:19]
	v_pk_fma_f32 v[50:51], v[158:159], v[20:21], v[50:51]
	v_add_f32_dpp v48, v48, v48 row_ror:4 row_mask:0xf bank_mask:0xf bound_ctrl:1
	v_add_f32_e32 v185, v50, v51
	ds_read_b128 v[140:143], v31 offset:2048
	v_add_f32_dpp v48, v48, v48 row_ror:2 row_mask:0xf bank_mask:0xf bound_ctrl:1
	ds_read_b128 v[144:147], v31 offset:6144
	ds_read_b128 v[148:151], v31 offset:10240
	v_add_f32_dpp v48, v48, v48 row_ror:1 row_mask:0xf bank_mask:0xf bound_ctrl:1
	ds_read_b128 v[152:155], v31 offset:14336
	ds_read_b128 v[156:159], v31 offset:18432
	v_pk_fma_f32 v[18:19], v[108:109], v[48:49], v[44:45] op_sel_hi:[1,0,1]
	v_pk_fma_f32 v[20:21], v[110:111], v[48:49], v[46:47] op_sel_hi:[1,0,1]
	s_waitcnt lgkmcnt(5)
	v_pk_mul_f32 v[42:43], v[134:135], v[20:21]
	v_pk_mul_f32 v[46:47], v[122:123], v[20:21]
	v_pk_fma_f32 v[42:43], v[132:133], v[18:19], v[42:43]
	v_pk_mul_f32 v[44:45], v[120:121], v[18:19]
	v_add_f32_e32 v48, v42, v43
	v_pk_fma_f32 v[44:45], v[124:125], v[170:171], v[44:45] op_sel:[0,1,0]
	v_pk_fma_f32 v[46:47], v[126:127], v[170:171], v[46:47] op_sel:[0,1,0]
	v_add_f32_dpp v48, v48, v48 row_ror:8 row_mask:0xf bank_mask:0xf bound_ctrl:1
	v_pk_mul_f32 v[50:51], v[116:117], v[18:19]
	v_pk_fma_f32 v[50:51], v[118:119], v[20:21], v[50:51]
	v_add_f32_dpp v48, v48, v48 row_ror:4 row_mask:0xf bank_mask:0xf bound_ctrl:1
	v_add_f32_e32 v186, v50, v51
	ds_read_b128 v[100:103], v31 offset:2304
	v_add_f32_dpp v48, v48, v48 row_ror:2 row_mask:0xf bank_mask:0xf bound_ctrl:1
	ds_read_b128 v[104:107], v31 offset:6400
	ds_read_b128 v[108:111], v31 offset:10496
	v_add_f32_dpp v48, v48, v48 row_ror:1 row_mask:0xf bank_mask:0xf bound_ctrl:1
	ds_read_b128 v[112:115], v31 offset:14592
	ds_read_b128 v[116:119], v31 offset:18688
	v_pk_fma_f32 v[18:19], v[128:129], v[48:49], v[44:45] op_sel_hi:[1,0,1]
	v_pk_fma_f32 v[20:21], v[130:131], v[48:49], v[46:47] op_sel_hi:[1,0,1]
	s_waitcnt lgkmcnt(5)
	v_pk_mul_f32 v[42:43], v[154:155], v[20:21]
	v_pk_mul_f32 v[46:47], v[142:143], v[20:21]
	v_pk_fma_f32 v[42:43], v[152:153], v[18:19], v[42:43]
	v_pk_mul_f32 v[44:45], v[140:141], v[18:19]
	v_add_f32_e32 v48, v42, v43
	v_pk_fma_f32 v[44:45], v[144:145], v[172:173], v[44:45] op_sel_hi:[1,0,1]
	v_pk_fma_f32 v[46:47], v[146:147], v[172:173], v[46:47] op_sel_hi:[1,0,1]
	v_add_f32_dpp v48, v48, v48 row_ror:8 row_mask:0xf bank_mask:0xf bound_ctrl:1
	v_pk_mul_f32 v[50:51], v[136:137], v[18:19]
	v_pk_fma_f32 v[50:51], v[138:139], v[20:21], v[50:51]
	v_add_f32_dpp v48, v48, v48 row_ror:4 row_mask:0xf bank_mask:0xf bound_ctrl:1
	v_add_f32_e32 v187, v50, v51
	ds_read_b128 v[120:123], v31 offset:2560
	v_add_f32_dpp v48, v48, v48 row_ror:2 row_mask:0xf bank_mask:0xf bound_ctrl:1
	ds_read_b128 v[124:127], v31 offset:6656
	ds_read_b128 v[128:131], v31 offset:10752
	v_add_f32_dpp v48, v48, v48 row_ror:1 row_mask:0xf bank_mask:0xf bound_ctrl:1
	ds_read_b128 v[132:135], v31 offset:14848
	ds_read_b128 v[136:139], v31 offset:18944
	v_pk_fma_f32 v[18:19], v[148:149], v[48:49], v[44:45] op_sel_hi:[1,0,1]
	v_pk_fma_f32 v[20:21], v[150:151], v[48:49], v[46:47] op_sel_hi:[1,0,1]
	s_waitcnt lgkmcnt(5)
; DI void phase_scan(const Params& p, char* smem) {
;     ...
;     for (int s = 0; s < CH; ++s) {
;       const float4 fw = fwv[s % 3], fk = fkv[s % 3], fb = fbv[s % 3], fa = fav[s % 3], fr = frv[s % 3];
;       const float vv = vvv[s % 3];
;       const float2_t a01 = {fa.x, fa.y}, a23 = {fa.z, fa.w};
;       const float2_t w01 = {fw.x, fw.y}, w23 = {fw.z, fw.w}, k01 = {fk.x, fk.y}, k23 = {fk.z, fk.w}, b01 = {fb.x, fb.y}, b23 = {fb.z, fb.w};
;       const float2_t r01 = {fr.x, fr.y}, r23 = {fr.z, fr.w};
;       const float2_t vv2 = {vv, vv};
;       if (s + 2 < CH) {
;         constexpr int dummy = 0; (void)dummy;
;         const int q = (s + 2) % 3;
;         fwv[q] = *(const float4*)(bl + 0 * CH * 64 + (s + 2) * 64); fkv[q] = *(const float4*)(bl + 1 * CH * 64 + (s + 2) * 64); fbv[q] = *(const float4*)(bl + 2 * CH * 64 + (s + 2) * 64);
;         fav[q] = *(const float4*)(bl + 3 * CH * 64 + (s + 2) * 64); frv[q] = *(const float4*)(bl + 4 * CH * 64 + (s + 2) * 64); vvv[q] = bv[(s + 2) * 16];
;       }
;       float2_t t2 = S01 * a01; t2 = S23 * a23 + t2;
;       const float2_t q01 = S01 * w01 + vv2 * k01, q23 = S23 * w23 + vv2 * k23;
;       float xs = t2.x + t2.y, ys = ypart;
;       xs += __builtin_bit_cast(float, __builtin_amdgcn_update_dpp(0, __builtin_bit_cast(int, xs), 0x128, 0xf, 0xf, false));
;       ys += __builtin_bit_cast(float, __builtin_amdgcn_update_dpp(0, __builtin_bit_cast(int, ys), 0x128, 0xf, 0xf, false));
;       xs += __builtin_bit_cast(float, __builtin_amdgcn_update_dpp(0, __builtin_bit_cast(int, xs), 0x124, 0xf, 0xf, false));
;       ys += __builtin_bit_cast(float, __builtin_amdgcn_update_dpp(0, __builtin_bit_cast(int, ys), 0x124, 0xf, 0xf, false));
;       xs += __builtin_bit_cast(float, __builtin_amdgcn_update_dpp(0, __builtin_bit_cast(int, xs), 0x122, 0xf, 0xf, false));
;       ys += __builtin_bit_cast(float, __builtin_amdgcn_update_dpp(0, __builtin_bit_cast(int, ys), 0x122, 0xf, 0xf, false));
;       xs += __builtin_bit_cast(float, __builtin_amdgcn_update_dpp(0, __builtin_bit_cast(int, xs), 0x121, 0xf, 0xf, false));
;       ys += __builtin_bit_cast(float, __builtin_amdgcn_update_dpp(0, __builtin_bit_cast(int, ys), 0x121, 0xf, 0xf, false));
;       if (s > 0) ysel = (kq == s - 1) ? ys : ysel;
;       const float2_t sa2 = {xs, xs};
;       S01 = sa2 * b01 + q01; S23 = sa2 * b23 + q23;
;       float2_t y2 = S01 * r01; y2 = S23 * r23 + y2;
	v_pk_mul_f32 v[42:43], v[114:115], v[20:21]
	v_pk_mul_f32 v[46:47], v[102:103], v[20:21]
	v_pk_fma_f32 v[42:43], v[112:113], v[18:19], v[42:43]
	v_pk_mul_f32 v[44:45], v[100:101], v[18:19]
	v_add_f32_e32 v48, v42, v43
	v_pk_fma_f32 v[44:45], v[104:105], v[172:173], v[44:45] op_sel:[0,1,0]
	v_pk_fma_f32 v[46:47], v[106:107], v[172:173], v[46:47] op_sel:[0,1,0]
	v_add_f32_dpp v48, v48, v48 row_ror:8 row_mask:0xf bank_mask:0xf bound_ctrl:1
	v_pk_mul_f32 v[50:51], v[156:157], v[18:19]
	v_pk_fma_f32 v[50:51], v[158:159], v[20:21], v[50:51]
	v_add_f32_dpp v48, v48, v48 row_ror:4 row_mask:0xf bank_mask:0xf bound_ctrl:1
	v_add_f32_e32 v188, v50, v51
	ds_read_b128 v[140:143], v31 offset:2816
	v_add_f32_dpp v48, v48, v48 row_ror:2 row_mask:0xf bank_mask:0xf bound_ctrl:1
	ds_read_b128 v[144:147], v31 offset:6912
	ds_read_b128 v[148:151], v31 offset:11008
	v_add_f32_dpp v48, v48, v48 row_ror:1 row_mask:0xf bank_mask:0xf bound_ctrl:1
	ds_read_b128 v[152:155], v31 offset:15104
	ds_read_b128 v[156:159], v31 offset:19200
	v_pk_fma_f32 v[18:19], v[108:109], v[48:49], v[44:45] op_sel_hi:[1,0,1]
	v_pk_fma_f32 v[20:21], v[110:111], v[48:49], v[46:47] op_sel_hi:[1,0,1]
	s_waitcnt lgkmcnt(5)
	v_pk_mul_f32 v[42:43], v[134:135], v[20:21]
	v_pk_mul_f32 v[46:47], v[122:123], v[20:21]
	v_pk_fma_f32 v[42:43], v[132:133], v[18:19], v[42:43]
	v_pk_mul_f32 v[44:45], v[120:121], v[18:19]
	v_add_f32_e32 v48, v42, v43
	v_pk_fma_f32 v[44:45], v[124:125], v[174:175], v[44:45] op_sel_hi:[1,0,1]
	v_pk_fma_f32 v[46:47], v[126:127], v[174:175], v[46:47] op_sel_hi:[1,0,1]
	v_add_f32_dpp v48, v48, v48 row_ror:8 row_mask:0xf bank_mask:0xf bound_ctrl:1
	v_pk_mul_f32 v[50:51], v[116:117], v[18:19]
	v_pk_fma_f32 v[50:51], v[118:119], v[20:21], v[50:51]
	v_add_f32_dpp v48, v48, v48 row_ror:4 row_mask:0xf bank_mask:0xf bound_ctrl:1
	v_add_f32_e32 v189, v50, v51
	ds_read_b128 v[100:103], v31 offset:3072
	v_add_f32_dpp v48, v48, v48 row_ror:2 row_mask:0xf bank_mask:0xf bound_ctrl:1
	ds_read_b128 v[104:107], v31 offset:7168
	ds_read_b128 v[108:111], v31 offset:11264
	v_add_f32_dpp v48, v48, v48 row_ror:1 row_mask:0xf bank_mask:0xf bound_ctrl:1
	ds_read_b128 v[112:115], v31 offset:15360
	ds_read_b128 v[116:119], v31 offset:19456
	v_pk_fma_f32 v[18:19], v[128:129], v[48:49], v[44:45] op_sel_hi:[1,0,1]
	v_pk_fma_f32 v[20:21], v[130:131], v[48:49], v[46:47] op_sel_hi:[1,0,1]
	s_waitcnt lgkmcnt(5)
	v_pk_mul_f32 v[42:43], v[154:155], v[20:21]
	v_pk_mul_f32 v[46:47], v[142:143], v[20:21]
	v_pk_fma_f32 v[42:43], v[152:153], v[18:19], v[42:43]
	v_pk_mul_f32 v[44:45], v[140:141], v[18:19]
	v_add_f32_e32 v48, v42, v43
	v_pk_fma_f32 v[44:45], v[144:145], v[174:175], v[44:45] op_sel:[0,1,0]
	v_pk_fma_f32 v[46:47], v[146:147], v[174:175], v[46:47] op_sel:[0,1,0]
	v_add_f32_dpp v48, v48, v48 row_ror:8 row_mask:0xf bank_mask:0xf bound_ctrl:1
	v_pk_mul_f32 v[50:51], v[136:137], v[18:19]
	v_pk_fma_f32 v[50:51], v[138:139], v[20:21], v[50:51]
	v_add_f32_dpp v48, v48, v48 row_ror:4 row_mask:0xf bank_mask:0xf bound_ctrl:1
	v_add_f32_e32 v190, v50, v51
	ds_read_b128 v[120:123], v31 offset:3328
	v_add_f32_dpp v48, v48, v48 row_ror:2 row_mask:0xf bank_mask:0xf bound_ctrl:1
	ds_read_b128 v[124:127], v31 offset:7424
	ds_read_b128 v[128:131], v31 offset:11520
	v_add_f32_dpp v48, v48, v48 row_ror:1 row_mask:0xf bank_mask:0xf bound_ctrl:1
	ds_read_b128 v[132:135], v31 offset:15616
	ds_read_b128 v[136:139], v31 offset:19712
	v_pk_fma_f32 v[18:19], v[148:149], v[48:49], v[44:45] op_sel_hi:[1,0,1]
	v_pk_fma_f32 v[20:21], v[150:151], v[48:49], v[46:47] op_sel_hi:[1,0,1]
	s_waitcnt lgkmcnt(5)
	v_pk_mul_f32 v[42:43], v[114:115], v[20:21]
	v_pk_mul_f32 v[46:47], v[102:103], v[20:21]
	v_pk_fma_f32 v[42:43], v[112:113], v[18:19], v[42:43]
	v_pk_mul_f32 v[44:45], v[100:101], v[18:19]
	v_add_f32_e32 v48, v42, v43
	v_pk_fma_f32 v[44:45], v[104:105], v[176:177], v[44:45] op_sel_hi:[1,0,1]
	v_pk_fma_f32 v[46:47], v[106:107], v[176:177], v[46:47] op_sel_hi:[1,0,1]
	v_add_f32_dpp v48, v48, v48 row_ror:8 row_mask:0xf bank_mask:0xf bound_ctrl:1
	v_pk_mul_f32 v[50:51], v[156:157], v[18:19]
	v_pk_fma_f32 v[50:51], v[158:159], v[20:21], v[50:51]
	v_add_f32_dpp v48, v48, v48 row_ror:4 row_mask:0xf bank_mask:0xf bound_ctrl:1
	v_add_f32_e32 v191, v50, v51
	ds_read_b128 v[140:143], v31 offset:3584
	v_add_f32_dpp v48, v48, v48 row_ror:2 row_mask:0xf bank_mask:0xf bound_ctrl:1
	ds_read_b128 v[144:147], v31 offset:7680
	ds_read_b128 v[148:151], v31 offset:11776
	v_add_f32_dpp v48, v48, v48 row_ror:1 row_mask:0xf bank_mask:0xf bound_ctrl:1
	ds_read_b128 v[152:155], v31 offset:15872
	ds_read_b128 v[156:159], v31 offset:19968
	v_pk_fma_f32 v[18:19], v[108:109], v[48:49], v[44:45] op_sel_hi:[1,0,1]
	v_pk_fma_f32 v[20:21], v[110:111], v[48:49], v[46:47] op_sel_hi:[1,0,1]
	s_waitcnt lgkmcnt(5)
	v_pk_mul_f32 v[42:43], v[134:135], v[20:21]
	v_pk_mul_f32 v[46:47], v[122:123], v[20:21]
	v_pk_fma_f32 v[42:43], v[132:133], v[18:19], v[42:43]
	v_pk_mul_f32 v[44:45], v[120:121], v[18:19]
	v_add_f32_e32 v48, v42, v43
	v_pk_fma_f32 v[44:45], v[124:125], v[176:177], v[44:45] op_sel:[0,1,0]
	v_pk_fma_f32 v[46:47], v[126:127], v[176:177], v[46:47] op_sel:[0,1,0]
	v_add_f32_dpp v48, v48, v48 row_ror:8 row_mask:0xf bank_mask:0xf bound_ctrl:1
	v_pk_mul_f32 v[50:51], v[116:117], v[18:19]
	v_pk_fma_f32 v[50:51], v[118:119], v[20:21], v[50:51]
	v_add_f32_dpp v48, v48, v48 row_ror:4 row_mask:0xf bank_mask:0xf bound_ctrl:1
	v_add_f32_e32 v192, v50, v51
	ds_read_b128 v[100:103], v31 offset:3840
	v_add_f32_dpp v48, v48, v48 row_ror:2 row_mask:0xf bank_mask:0xf bound_ctrl:1
	ds_read_b128 v[104:107], v31 offset:7936
	ds_read_b128 v[108:111], v31 offset:12032
	v_add_f32_dpp v48, v48, v48 row_ror:1 row_mask:0xf bank_mask:0xf bound_ctrl:1
	ds_read_b128 v[112:115], v31 offset:16128
	ds_read_b128 v[116:119], v31 offset:20224
	v_pk_fma_f32 v[18:19], v[128:129], v[48:49], v[44:45] op_sel_hi:[1,0,1]
	v_pk_fma_f32 v[20:21], v[130:131], v[48:49], v[46:47] op_sel_hi:[1,0,1]
	s_waitcnt lgkmcnt(5)
; DI u16 f2bf(float a) { return (u16)(pack2(a, 0.f) & 0xffffu); }
; DI void phase_scan(const Params& p, char* smem) {
;     ...
;       float2_t t2 = S01 * a01; t2 = S23 * a23 + t2;
;       const float2_t q01 = S01 * w01 + vv2 * k01, q23 = S23 * w23 + vv2 * k23;
;       float xs = t2.x + t2.y, ys = ypart;
;       xs += __builtin_bit_cast(float, __builtin_amdgcn_update_dpp(0, __builtin_bit_cast(int, xs), 0x128, 0xf, 0xf, false));
;       ys += __builtin_bit_cast(float, __builtin_amdgcn_update_dpp(0, __builtin_bit_cast(int, ys), 0x128, 0xf, 0xf, false));
;       xs += __builtin_bit_cast(float, __builtin_amdgcn_update_dpp(0, __builtin_bit_cast(int, xs), 0x124, 0xf, 0xf, false));
;       ys += __builtin_bit_cast(float, __builtin_amdgcn_update_dpp(0, __builtin_bit_cast(int, ys), 0x124, 0xf, 0xf, false));
;       xs += __builtin_bit_cast(float, __builtin_amdgcn_update_dpp(0, __builtin_bit_cast(int, xs), 0x122, 0xf, 0xf, false));
;       ys += __builtin_bit_cast(float, __builtin_amdgcn_update_dpp(0, __builtin_bit_cast(int, ys), 0x122, 0xf, 0xf, false));
;       xs += __builtin_bit_cast(float, __builtin_amdgcn_update_dpp(0, __builtin_bit_cast(int, xs), 0x121, 0xf, 0xf, false));
;       ys += __builtin_bit_cast(float, __builtin_amdgcn_update_dpp(0, __builtin_bit_cast(int, ys), 0x121, 0xf, 0xf, false));
;       if (s > 0) ysel = (kq == s - 1) ? ys : ysel;
;       const float2_t sa2 = {xs, xs};
;       S01 = sa2 * b01 + q01; S23 = sa2 * b23 + q23;
;       float2_t y2 = S01 * r01; y2 = S23 * r23 + y2;
;       ypart = y2.x + y2.y;
;     }
;     { const float yl = rowsum16(ypart); ysel = (kq == CH - 1) ? yl : ysel; }
;     Y[(size_t)(rowbase + rstep * kq) * 256 + h * 64 + vrow] = f2bf(ysel);
;     if (c + 1 < NCH) SCAN_LSTORE((c + 1) & 1);
	v_pk_mul_f32 v[42:43], v[154:155], v[20:21]
	v_pk_mul_f32 v[46:47], v[142:143], v[20:21]
	v_pk_fma_f32 v[42:43], v[152:153], v[18:19], v[42:43]
	v_pk_mul_f32 v[44:45], v[140:141], v[18:19]
	v_add_f32_e32 v48, v42, v43
	v_pk_fma_f32 v[44:45], v[144:145], v[178:179], v[44:45] op_sel_hi:[1,0,1]
	v_pk_fma_f32 v[46:47], v[146:147], v[178:179], v[46:47] op_sel_hi:[1,0,1]
	v_add_f32_dpp v48, v48, v48 row_ror:8 row_mask:0xf bank_mask:0xf bound_ctrl:1
	v_pk_mul_f32 v[50:51], v[136:137], v[18:19]
	v_pk_fma_f32 v[50:51], v[138:139], v[20:21], v[50:51]
	v_add_f32_dpp v48, v48, v48 row_ror:4 row_mask:0xf bank_mask:0xf bound_ctrl:1
	v_add_f32_e32 v193, v50, v51
	s_nop 0
	v_add_f32_dpp v48, v48, v48 row_ror:2 row_mask:0xf bank_mask:0xf bound_ctrl:1
	s_nop 1
	v_add_f32_dpp v48, v48, v48 row_ror:1 row_mask:0xf bank_mask:0xf bound_ctrl:1
	v_pk_fma_f32 v[18:19], v[148:149], v[48:49], v[44:45] op_sel_hi:[1,0,1]
	v_pk_fma_f32 v[20:21], v[150:151], v[48:49], v[46:47] op_sel_hi:[1,0,1]
	s_waitcnt lgkmcnt(0)
	v_pk_mul_f32 v[42:43], v[114:115], v[20:21]
	v_pk_mul_f32 v[46:47], v[102:103], v[20:21]
	v_pk_fma_f32 v[42:43], v[112:113], v[18:19], v[42:43]
	v_pk_mul_f32 v[44:45], v[100:101], v[18:19]
	v_add_f32_e32 v48, v42, v43
	v_pk_fma_f32 v[44:45], v[104:105], v[178:179], v[44:45] op_sel:[0,1,0]
	v_pk_fma_f32 v[46:47], v[106:107], v[178:179], v[46:47] op_sel:[0,1,0]
	v_add_f32_dpp v48, v48, v48 row_ror:8 row_mask:0xf bank_mask:0xf bound_ctrl:1
	v_pk_mul_f32 v[50:51], v[156:157], v[18:19]
	v_pk_fma_f32 v[50:51], v[158:159], v[20:21], v[50:51]
	v_add_f32_dpp v48, v48, v48 row_ror:4 row_mask:0xf bank_mask:0xf bound_ctrl:1
	v_add_f32_e32 v194, v50, v51
	s_nop 0
	v_add_f32_dpp v48, v48, v48 row_ror:2 row_mask:0xf bank_mask:0xf bound_ctrl:1
	s_nop 1
	v_add_f32_dpp v48, v48, v48 row_ror:1 row_mask:0xf bank_mask:0xf bound_ctrl:1
	v_pk_fma_f32 v[18:19], v[108:109], v[48:49], v[44:45] op_sel_hi:[1,0,1]
	v_pk_fma_f32 v[20:21], v[110:111], v[48:49], v[46:47] op_sel_hi:[1,0,1]
	v_pk_mul_f32 v[50:51], v[116:117], v[18:19]
	v_pk_fma_f32 v[50:51], v[118:119], v[20:21], v[50:51]
	v_add_f32_e32 v195, v50, v51
	v_add_f32_dpp v60, v180, v180 row_ror:8 row_mask:0xf bank_mask:0x3 bound_ctrl:1
	v_add_f32_dpp v61, v181, v181 row_ror:8 row_mask:0xf bank_mask:0x3 bound_ctrl:1
	v_add_f32_dpp v62, v182, v182 row_ror:8 row_mask:0xf bank_mask:0x3 bound_ctrl:1
	v_add_f32_dpp v63, v183, v183 row_ror:8 row_mask:0xf bank_mask:0x3 bound_ctrl:1
	v_add_f32_dpp v64, v184, v184 row_ror:8 row_mask:0xf bank_mask:0x3 bound_ctrl:1
	v_add_f32_dpp v65, v185, v185 row_ror:8 row_mask:0xf bank_mask:0x3 bound_ctrl:1
	v_add_f32_dpp v66, v186, v186 row_ror:8 row_mask:0xf bank_mask:0x3 bound_ctrl:1
	v_add_f32_dpp v67, v187, v187 row_ror:8 row_mask:0xf bank_mask:0x3 bound_ctrl:1
	v_add_f32_dpp v60, v188, v188 row_ror:8 row_mask:0xf bank_mask:0xc bound_ctrl:1
	v_add_f32_dpp v61, v189, v189 row_ror:8 row_mask:0xf bank_mask:0xc bound_ctrl:1
	v_add_f32_dpp v62, v190, v190 row_ror:8 row_mask:0xf bank_mask:0xc bound_ctrl:1
	v_add_f32_dpp v63, v191, v191 row_ror:8 row_mask:0xf bank_mask:0xc bound_ctrl:1
	v_add_f32_dpp v64, v192, v192 row_ror:8 row_mask:0xf bank_mask:0xc bound_ctrl:1
	v_add_f32_dpp v65, v193, v193 row_ror:8 row_mask:0xf bank_mask:0xc bound_ctrl:1
	v_add_f32_dpp v66, v194, v194 row_ror:8 row_mask:0xf bank_mask:0xc bound_ctrl:1
	v_add_f32_dpp v67, v195, v195 row_ror:8 row_mask:0xf bank_mask:0xc bound_ctrl:1
	v_add_f32_dpp v68, v60, v60 row_half_mirror row_mask:0xf bank_mask:0x5 bound_ctrl:1
	v_add_f32_dpp v69, v61, v61 row_half_mirror row_mask:0xf bank_mask:0x5 bound_ctrl:1
	v_add_f32_dpp v70, v62, v62 row_half_mirror row_mask:0xf bank_mask:0x5 bound_ctrl:1
	v_add_f32_dpp v71, v63, v63 row_half_mirror row_mask:0xf bank_mask:0x5 bound_ctrl:1
	v_add_f32_dpp v68, v64, v64 row_half_mirror row_mask:0xf bank_mask:0xa bound_ctrl:1
	v_add_f32_dpp v69, v65, v65 row_half_mirror row_mask:0xf bank_mask:0xa bound_ctrl:1
	v_add_f32_dpp v70, v66, v66 row_half_mirror row_mask:0xf bank_mask:0xa bound_ctrl:1
	v_add_f32_dpp v71, v67, v67 row_half_mirror row_mask:0xf bank_mask:0xa bound_ctrl:1
	v_cndmask_b32_e64 v52, v70, v68, s[8:9]
	v_cndmask_b32_e64 v53, v68, v70, s[8:9]
	v_cndmask_b32_e64 v54, v71, v69, s[8:9]
	v_cndmask_b32_e64 v55, v69, v71, s[8:9]
	v_add_f32_dpp v72, v52, v53 quad_perm:[3,2,1,0] row_mask:0xf bank_mask:0xf bound_ctrl:1
	v_add_f32_dpp v73, v54, v55 quad_perm:[3,2,1,0] row_mask:0xf bank_mask:0xf bound_ctrl:1
	v_cndmask_b32_e64 v52, v73, v72, s[10:11]
	v_cndmask_b32_e64 v53, v72, v73, s[10:11]
	s_nop 1
	v_add_f32_dpp v31, v52, v53 quad_perm:[1,0,3,2] row_mask:0xf bank_mask:0xf bound_ctrl:1
	v_cvt_pk_bf16_f32 v32, v31, s0
	v_ashrrev_i32_e32 v31, 31, v30
	v_lshlrev_b64 v[30:31], 9, v[30:31]
	v_lshl_add_u64 v[30:31], v[16:17], 0, v[30:31]
	flat_store_short v[30:31], v32
	s_cbranch_vccnz .LBB0_507
	s_bitcmp1_b32 s96, 0
	s_cselect_b32 s46, 0x5400, 0
	s_waitcnt vmcnt(0)
	v_lshlrev_b32_e32 v30, 16, v4
	v_and_b32_e32 v31, 0xffff0000, v4
	v_lshlrev_b32_e32 v32, 16, v5
	v_and_b32_e32 v33, 0xffff0000, v5
	v_add_u32_e32 v34, s46, v26
	v_pk_add_f32 v[30:31], v[30:31], 1.0 op_sel_hi:[1,0] neg_lo:[1,0] neg_hi:[1,0]
	v_pk_add_f32 v[32:33], v[32:33], 1.0 op_sel_hi:[1,0] neg_lo:[1,0] neg_hi:[1,0]
	ds_write_b128 v34, v[30:33]
	v_lshlrev_b32_e32 v30, 16, v6
	v_and_b32_e32 v31, 0xffff0000, v6
	v_lshlrev_b32_e32 v32, 16, v7
	v_and_b32_e32 v33, 0xffff0000, v7
	ds_write_b128 v34, v[30:33] offset:4096
	v_lshlrev_b32_e32 v30, 16, v8
	v_and_b32_e32 v31, 0xffff0000, v8
	v_lshlrev_b32_e32 v32, 16, v9
	v_and_b32_e32 v33, 0xffff0000, v9
	ds_write_b128 v34, v[30:33] offset:8192
	v_lshlrev_b32_e32 v30, 16, v10
	v_and_b32_e32 v31, 0xffff0000, v10
	v_lshlrev_b32_e32 v32, 16, v11
	v_and_b32_e32 v33, 0xffff0000, v11
	ds_write_b128 v34, v[30:33] offset:12288
	v_lshlrev_b32_e32 v30, 16, v12
	v_and_b32_e32 v31, 0xffff0000, v12
	v_lshlrev_b32_e32 v32, 16, v13
	v_and_b32_e32 v33, 0xffff0000, v13
	ds_write_b128 v34, v[30:33] offset:16384
	v_lshlrev_b32_e32 v30, 16, v27
	v_add_u32_e32 v31, s46, v28
	ds_write_b32 v31, v30 offset:20480
	s_branch .LBB0_507
